# prompt attention output store: transpose through per-wave LDS scratch, 4 dwordx4 full-line stores per wave instead of 32 two-byte stores; one LDS read of the 16 row scales
# speedup vs baseline: 1.0074x; 1.0074x over previous
.LBB0_753:
	s_or_b64 exec, exec, s[2:3]
	s_waitcnt lgkmcnt(0)
	v_readlane_b32 s100, v253, 22
	v_readlane_b32 s101, v253, 23
	v_and_b32_e32 v48, 63, v0
	v_lshrrev_b32_e32 v49, 5, v48
	v_and_b32_e32 v50, 31, v48
	v_lshl_add_u32 v51, v49, 4, s78
	ds_read2_b32 v[52:53], v51 offset1:1
	ds_read2_b32 v[54:55], v51 offset0:2 offset1:3
	ds_read2_b32 v[56:57], v51 offset0:8 offset1:9
	ds_read2_b32 v[58:59], v51 offset0:10 offset1:11
	ds_read2_b32 v[60:61], v51 offset0:16 offset1:17
	ds_read2_b32 v[62:63], v51 offset0:18 offset1:19
	ds_read2_b32 v[64:65], v51 offset0:24 offset1:25
	ds_read2_b32 v[66:67], v51 offset0:26 offset1:27
	v_lshrrev_b32_e32 v68, 6, v0
	v_lshlrev_b32_e32 v68, 12, v68
	v_add_u32_e32 v68, 0x11000, v68
	v_lshl_add_u32 v69, v49, 9, v68
	v_lshl_add_u32 v69, v50, 1, v69
	v_lshrrev_b32_e32 v70, 3, v48
	v_and_b32_e32 v71, 7, v48
	v_lshl_add_u32 v72, v70, 7, v68
	v_lshl_add_u32 v72, v71, 4, v72
	v_mov_b32_e32 v74, v70
	v_mov_b32_e32 v75, 0
	v_lshl_add_u64 v[74:75], s[12:13], 0, v[74:75]
	v_lshlrev_b64 v[74:75], 11, v[74:75]
	v_lshl_add_u64 v[74:75], s[100:101], 0, v[74:75]
	v_lshlrev_b32_e32 v82, 4, v71
	v_mov_b32_e32 v83, 0
	v_lshl_add_u64 v[74:75], v[74:75], 0, v[82:83]
	v_mov_b32_e32 v82, 0x4000
	v_lshl_add_u64 v[76:77], v[74:75], 0, v[82:83]
	v_lshl_add_u64 v[78:79], v[76:77], 0, v[82:83]
	v_lshl_add_u64 v[80:81], v[78:79], 0, v[82:83]
	s_waitcnt lgkmcnt(0)
	v_mul_f32_e32 v1, v32, v52
	v_mul_f32_e32 v2, v16, v52
	v_cvt_pk_bf16_f32 v1, v1, v15
	v_cvt_pk_bf16_f32 v2, v2, v15
	ds_write_b16 v69, v1
	ds_write_b16 v69, v2 offset:64
	v_mul_f32_e32 v1, v33, v53
	v_mul_f32_e32 v2, v17, v53
	v_cvt_pk_bf16_f32 v1, v1, v15
	v_cvt_pk_bf16_f32 v2, v2, v15
	ds_write_b16 v69, v1 offset:128
	ds_write_b16 v69, v2 offset:192
	v_mul_f32_e32 v1, v34, v54
	v_mul_f32_e32 v2, v18, v54
	v_cvt_pk_bf16_f32 v1, v1, v15
	v_cvt_pk_bf16_f32 v2, v2, v15
	ds_write_b16 v69, v1 offset:256
	ds_write_b16 v69, v2 offset:320
	v_mul_f32_e32 v1, v35, v55
	v_mul_f32_e32 v2, v19, v55
	v_cvt_pk_bf16_f32 v1, v1, v15
	v_cvt_pk_bf16_f32 v2, v2, v15
	ds_write_b16 v69, v1 offset:384
	ds_write_b16 v69, v2 offset:448
	v_mul_f32_e32 v1, v36, v56
	v_mul_f32_e32 v2, v20, v56
	v_cvt_pk_bf16_f32 v1, v1, v15
	v_cvt_pk_bf16_f32 v2, v2, v15
	ds_write_b16 v69, v1 offset:1024
	ds_write_b16 v69, v2 offset:1088
	v_mul_f32_e32 v1, v37, v57
	v_mul_f32_e32 v2, v21, v57
	v_cvt_pk_bf16_f32 v1, v1, v15
	v_cvt_pk_bf16_f32 v2, v2, v15
	ds_write_b16 v69, v1 offset:1152
	ds_write_b16 v69, v2 offset:1216
	v_mul_f32_e32 v1, v38, v58
	v_mul_f32_e32 v2, v22, v58
	v_cvt_pk_bf16_f32 v1, v1, v15
	v_cvt_pk_bf16_f32 v2, v2, v15
	ds_write_b16 v69, v1 offset:1280
	ds_write_b16 v69, v2 offset:1344
	v_mul_f32_e32 v1, v39, v59
	v_mul_f32_e32 v2, v23, v59
	v_cvt_pk_bf16_f32 v1, v1, v15
	v_cvt_pk_bf16_f32 v2, v2, v15
	ds_write_b16 v69, v1 offset:1408
	ds_write_b16 v69, v2 offset:1472
	v_mul_f32_e32 v1, v40, v60
	v_mul_f32_e32 v2, v24, v60
	v_cvt_pk_bf16_f32 v1, v1, v15
	v_cvt_pk_bf16_f32 v2, v2, v15
	ds_write_b16 v69, v1 offset:2048
	ds_write_b16 v69, v2 offset:2112
	v_mul_f32_e32 v1, v41, v61
	v_mul_f32_e32 v2, v25, v61
	v_cvt_pk_bf16_f32 v1, v1, v15
	v_cvt_pk_bf16_f32 v2, v2, v15
	ds_write_b16 v69, v1 offset:2176
	ds_write_b16 v69, v2 offset:2240
	v_mul_f32_e32 v1, v42, v62
	v_mul_f32_e32 v2, v26, v62
	v_cvt_pk_bf16_f32 v1, v1, v15
	v_cvt_pk_bf16_f32 v2, v2, v15
	ds_write_b16 v69, v1 offset:2304
	ds_write_b16 v69, v2 offset:2368
	v_mul_f32_e32 v1, v43, v63
	v_mul_f32_e32 v2, v27, v63
	v_cvt_pk_bf16_f32 v1, v1, v15
	v_cvt_pk_bf16_f32 v2, v2, v15
	ds_write_b16 v69, v1 offset:2432
	ds_write_b16 v69, v2 offset:2496
	v_mul_f32_e32 v1, v44, v64
	v_mul_f32_e32 v2, v28, v64
	v_cvt_pk_bf16_f32 v1, v1, v15
	v_cvt_pk_bf16_f32 v2, v2, v15
	ds_write_b16 v69, v1 offset:3072
	ds_write_b16 v69, v2 offset:3136
	v_mul_f32_e32 v1, v45, v65
	v_mul_f32_e32 v2, v29, v65
	v_cvt_pk_bf16_f32 v1, v1, v15
	v_cvt_pk_bf16_f32 v2, v2, v15
	ds_write_b16 v69, v1 offset:3200
	ds_write_b16 v69, v2 offset:3264
	v_mul_f32_e32 v1, v46, v66
	v_mul_f32_e32 v2, v30, v66
	v_cvt_pk_bf16_f32 v1, v1, v15
	v_cvt_pk_bf16_f32 v2, v2, v15
	ds_write_b16 v69, v1 offset:3328
	ds_write_b16 v69, v2 offset:3392
	v_mul_f32_e32 v1, v47, v67
	v_mul_f32_e32 v2, v31, v67
	v_cvt_pk_bf16_f32 v1, v1, v15
	v_cvt_pk_bf16_f32 v2, v2, v15
	ds_write_b16 v69, v1 offset:3456
	ds_write_b16 v69, v2 offset:3520
	s_waitcnt lgkmcnt(0)
	ds_read_b128 v[84:87], v72
	ds_read_b128 v[88:91], v72 offset:1024
	ds_read_b128 v[92:95], v72 offset:2048
	ds_read_b128 v[96:99], v72 offset:3072
	s_waitcnt lgkmcnt(3)
	global_store_dwordx4 v[74:75], v[84:87], off
	s_waitcnt lgkmcnt(2)
	global_store_dwordx4 v[76:77], v[88:91], off
	s_waitcnt lgkmcnt(1)
	global_store_dwordx4 v[78:79], v[92:95], off
	s_waitcnt lgkmcnt(0)
	global_store_dwordx4 v[80:81], v[96:99], off
	s_branch .Lattn_wide_done_a
	v_readlane_b32 s2, v253, 22
	v_and_b32_e32 v4, -4, v1
	v_lshlrev_b32_e32 v14, 1, v100
	v_readlane_b32 s3, v253, 23
	v_cmp_gt_i32_e32 vcc, 32, v4
	s_nop 0
	v_lshl_add_u64 v[2:3], s[2:3], 0, v[14:15]
	s_and_saveexec_b64 s[2:3], vcc
	s_cbranch_execz .LBB0_755
	v_lshl_add_u32 v5, v4, 2, s78
	ds_read_b32 v8, v5
	v_ashrrev_i32_e32 v5, 31, v4
	v_lshl_add_u64 v[6:7], s[12:13], 0, v[4:5]
	v_lshlrev_b64 v[6:7], 11, v[6:7]
	v_lshl_add_u64 v[6:7], v[2:3], 0, v[6:7]
	s_waitcnt lgkmcnt(0)
	v_mul_f32_e32 v5, v32, v8
	v_cvt_pk_bf16_f32 v5, v5, v15
	global_store_short v[6:7], v5, off
	v_mul_f32_e32 v5, v16, v8
	v_cvt_pk_bf16_f32 v5, v5, v15
	global_store_short v[6:7], v5, off offset:64

.Lattn_wide_done_a:
	s_waitcnt lgkmcnt(0)
	s_waitcnt vmcnt(0) lgkmcnt(0)
	s_barrier

.LBB0_1076:
	s_or_b64 exec, exec, s[0:1]
	s_waitcnt lgkmcnt(0)
	v_readlane_b32 s100, v253, 22
	v_readlane_b32 s101, v253, 23
	v_and_b32_e32 v48, 63, v0
	v_lshrrev_b32_e32 v49, 5, v48
	v_and_b32_e32 v50, 31, v48
	v_lshl_add_u32 v51, v49, 4, s78
	ds_read2_b32 v[52:53], v51 offset1:1
	ds_read2_b32 v[54:55], v51 offset0:2 offset1:3
	ds_read2_b32 v[56:57], v51 offset0:8 offset1:9
	ds_read2_b32 v[58:59], v51 offset0:10 offset1:11
	ds_read2_b32 v[60:61], v51 offset0:16 offset1:17
	ds_read2_b32 v[62:63], v51 offset0:18 offset1:19
	ds_read2_b32 v[64:65], v51 offset0:24 offset1:25
	ds_read2_b32 v[66:67], v51 offset0:26 offset1:27
	v_lshrrev_b32_e32 v68, 6, v0
	v_lshlrev_b32_e32 v68, 12, v68
	v_add_u32_e32 v68, 0x11000, v68
	v_lshl_add_u32 v69, v49, 9, v68
	v_lshl_add_u32 v69, v50, 1, v69
	v_lshrrev_b32_e32 v70, 3, v48
	v_and_b32_e32 v71, 7, v48
	v_lshl_add_u32 v72, v70, 7, v68
	v_lshl_add_u32 v72, v71, 4, v72
	v_mov_b32_e32 v74, v70
	v_mov_b32_e32 v75, 0
	v_lshl_add_u64 v[74:75], s[12:13], 0, v[74:75]
	v_lshlrev_b64 v[74:75], 11, v[74:75]
	v_lshl_add_u64 v[74:75], s[100:101], 0, v[74:75]
	v_lshlrev_b32_e32 v82, 4, v71
	v_mov_b32_e32 v83, 0
	v_lshl_add_u64 v[74:75], v[74:75], 0, v[82:83]
	v_mov_b32_e32 v82, 0x4000
	v_lshl_add_u64 v[76:77], v[74:75], 0, v[82:83]
	v_lshl_add_u64 v[78:79], v[76:77], 0, v[82:83]
	v_lshl_add_u64 v[80:81], v[78:79], 0, v[82:83]
	s_waitcnt lgkmcnt(0)
	v_mul_f32_e32 v1, v32, v52
	v_mul_f32_e32 v2, v16, v52
	v_cvt_pk_bf16_f32 v1, v1, v15
	v_cvt_pk_bf16_f32 v2, v2, v15
	ds_write_b16 v69, v1
	ds_write_b16 v69, v2 offset:64
	v_mul_f32_e32 v1, v33, v53
	v_mul_f32_e32 v2, v17, v53
	v_cvt_pk_bf16_f32 v1, v1, v15
	v_cvt_pk_bf16_f32 v2, v2, v15
	ds_write_b16 v69, v1 offset:128
	ds_write_b16 v69, v2 offset:192
	v_mul_f32_e32 v1, v34, v54
	v_mul_f32_e32 v2, v18, v54
	v_cvt_pk_bf16_f32 v1, v1, v15
	v_cvt_pk_bf16_f32 v2, v2, v15
	ds_write_b16 v69, v1 offset:256
	ds_write_b16 v69, v2 offset:320
	v_mul_f32_e32 v1, v35, v55
	v_mul_f32_e32 v2, v19, v55
	v_cvt_pk_bf16_f32 v1, v1, v15
	v_cvt_pk_bf16_f32 v2, v2, v15
	ds_write_b16 v69, v1 offset:384
	ds_write_b16 v69, v2 offset:448
	v_mul_f32_e32 v1, v36, v56
	v_mul_f32_e32 v2, v20, v56
	v_cvt_pk_bf16_f32 v1, v1, v15
	v_cvt_pk_bf16_f32 v2, v2, v15
	ds_write_b16 v69, v1 offset:1024
	ds_write_b16 v69, v2 offset:1088
	v_mul_f32_e32 v1, v37, v57
	v_mul_f32_e32 v2, v21, v57
	v_cvt_pk_bf16_f32 v1, v1, v15
	v_cvt_pk_bf16_f32 v2, v2, v15
	ds_write_b16 v69, v1 offset:1152
	ds_write_b16 v69, v2 offset:1216
	v_mul_f32_e32 v1, v38, v58
	v_mul_f32_e32 v2, v22, v58
	v_cvt_pk_bf16_f32 v1, v1, v15
	v_cvt_pk_bf16_f32 v2, v2, v15
	ds_write_b16 v69, v1 offset:1280
	ds_write_b16 v69, v2 offset:1344
	v_mul_f32_e32 v1, v39, v59
	v_mul_f32_e32 v2, v23, v59
	v_cvt_pk_bf16_f32 v1, v1, v15
	v_cvt_pk_bf16_f32 v2, v2, v15
	ds_write_b16 v69, v1 offset:1408
	ds_write_b16 v69, v2 offset:1472
	v_mul_f32_e32 v1, v40, v60
	v_mul_f32_e32 v2, v24, v60
	v_cvt_pk_bf16_f32 v1, v1, v15
	v_cvt_pk_bf16_f32 v2, v2, v15
	ds_write_b16 v69, v1 offset:2048
	ds_write_b16 v69, v2 offset:2112
	v_mul_f32_e32 v1, v41, v61
	v_mul_f32_e32 v2, v25, v61
	v_cvt_pk_bf16_f32 v1, v1, v15
	v_cvt_pk_bf16_f32 v2, v2, v15
	ds_write_b16 v69, v1 offset:2176
	ds_write_b16 v69, v2 offset:2240
	v_mul_f32_e32 v1, v42, v62
	v_mul_f32_e32 v2, v26, v62
	v_cvt_pk_bf16_f32 v1, v1, v15
	v_cvt_pk_bf16_f32 v2, v2, v15
	ds_write_b16 v69, v1 offset:2304
	ds_write_b16 v69, v2 offset:2368
	v_mul_f32_e32 v1, v43, v63
	v_mul_f32_e32 v2, v27, v63
	v_cvt_pk_bf16_f32 v1, v1, v15
	v_cvt_pk_bf16_f32 v2, v2, v15
	ds_write_b16 v69, v1 offset:2432
	ds_write_b16 v69, v2 offset:2496
	v_mul_f32_e32 v1, v44, v64
	v_mul_f32_e32 v2, v28, v64
	v_cvt_pk_bf16_f32 v1, v1, v15
	v_cvt_pk_bf16_f32 v2, v2, v15
	ds_write_b16 v69, v1 offset:3072
	ds_write_b16 v69, v2 offset:3136
	v_mul_f32_e32 v1, v45, v65
	v_mul_f32_e32 v2, v29, v65
	v_cvt_pk_bf16_f32 v1, v1, v15
	v_cvt_pk_bf16_f32 v2, v2, v15
	ds_write_b16 v69, v1 offset:3200
	ds_write_b16 v69, v2 offset:3264
	v_mul_f32_e32 v1, v46, v66
	v_mul_f32_e32 v2, v30, v66
	v_cvt_pk_bf16_f32 v1, v1, v15
	v_cvt_pk_bf16_f32 v2, v2, v15
	ds_write_b16 v69, v1 offset:3328
	ds_write_b16 v69, v2 offset:3392
	v_mul_f32_e32 v1, v47, v67
	v_mul_f32_e32 v2, v31, v67
	v_cvt_pk_bf16_f32 v1, v1, v15
	v_cvt_pk_bf16_f32 v2, v2, v15
	ds_write_b16 v69, v1 offset:3456
	ds_write_b16 v69, v2 offset:3520
	s_waitcnt lgkmcnt(0)
	ds_read_b128 v[84:87], v72
	ds_read_b128 v[88:91], v72 offset:1024
	ds_read_b128 v[92:95], v72 offset:2048
	ds_read_b128 v[96:99], v72 offset:3072
	s_waitcnt lgkmcnt(3)
	global_store_dwordx4 v[74:75], v[84:87], off
	s_waitcnt lgkmcnt(2)
	global_store_dwordx4 v[76:77], v[88:91], off
	s_waitcnt lgkmcnt(1)
	global_store_dwordx4 v[78:79], v[92:95], off
	s_waitcnt lgkmcnt(0)
	global_store_dwordx4 v[80:81], v[96:99], off
	s_branch .Lattn_wide_done_b
	v_readlane_b32 s0, v253, 22
	v_and_b32_e32 v4, -4, v1
	v_lshlrev_b32_e32 v14, 1, v105
	v_readlane_b32 s1, v253, 23
	v_cmp_gt_i32_e32 vcc, 32, v4
	s_nop 0
	v_lshl_add_u64 v[2:3], s[0:1], 0, v[14:15]
	s_and_saveexec_b64 s[0:1], vcc
	s_cbranch_execz .LBB0_1078
	v_lshl_add_u32 v5, v4, 2, s78
	ds_read_b32 v8, v5
	v_ashrrev_i32_e32 v5, 31, v4
	v_lshl_add_u64 v[6:7], s[12:13], 0, v[4:5]
	v_lshlrev_b64 v[6:7], 11, v[6:7]
	v_lshl_add_u64 v[6:7], v[2:3], 0, v[6:7]
	s_waitcnt lgkmcnt(0)
	v_mul_f32_e32 v5, v32, v8
	v_cvt_pk_bf16_f32 v5, v5, v15
	global_store_short v[6:7], v5, off
	v_mul_f32_e32 v5, v16, v8
	v_cvt_pk_bf16_f32 v5, v5, v15
	global_store_short v[6:7], v5, off offset:64
